# gla_finish_item: LDS spin barriers replaced by s_barrier
# baseline (speedup 1.0000x reference)
; DI int otid() { int t = threadIdx.x & 255; asm volatile("" : "+v"(t)); return t; }
; DI int VB() { return blockIdx.x * 2 + vhalf(); }
; DN void gla_finish_item(const Params& p, int l, int b, int cs, int hh, char* smem) {
;     ...
;   const int tid = otid(), lane = tid & 63, w = tid >> 6, r = lane & 31, h = lane >> 5;
;   const int et = w >> 1, it = w & 1;
;   const size_t m0 = (size_t)b * TT + cs * 64;
;   const int dl = tid & 31, lgrp = tid >> 5;
;   const int li4 = tid >> 2, d8 = (tid & 3) * 8;
;   f32x16 accO;
; #pragma unroll
;   for (int i = 0; i < 16; ++i) accO[i] = 0.f;
;   vsync();
; __global__ void __launch_bounds__(512, 2) fwd_megakernel(Params p) {
;     ...
;       for (int it = VB(); it < n_rwf + n_glaf; it += NVB()) {
;         if (it < n_rwf) {
;           int m0 = it * 16;
;           if (!need_ctx && (m0 % TT) >= TL) continue;
;           rw_finish_tile(p, l, it, smem);
;         } else {
;           int i2 = it - n_rwf;
;           int hh = i2 & 3, cs = (i2 >> 2) % 36, b = (i2 >> 2) / 36;
;           if (!need_ctx && cs >= 32) continue;
;           gla_finish_item(p, l, b, cs, hh, smem);
.LBB0_1002:
	s_cmpk_gt_i32 s12, 0x8ff
	s_mov_b64 s[2:3], -1
	s_cbranch_scc0 .LBB0_1093
	s_add_i32 s2, s12, 0xfffff700
	s_lshr_b32 s3, s2, 2
	s_mul_i32 s4, s3, 0xe38f
	s_lshr_b32 s4, s4, 21
	s_mul_i32 s4, s4, 36
	s_sub_i32 s8, s3, s4
	s_and_b32 s6, s8, 0xffff
	s_cmp_lt_u32 s6, 32
	s_cselect_b64 s[4:5], -1, 0
	s_or_b64 s[4:5], s[92:93], s[4:5]
	s_andn2_b64 vcc, exec, s[4:5]
	s_cbranch_vccnz .LBB0_1092
	s_mul_i32 s2, s2, 0xe38f
	s_lshr_b32 s7, s2, 23
	v_readfirstlane_b32 s2, v182
	s_lshr_b32 s9, s2, 8
	v_mov_b32_e32 v3, v183
	s_mov_b64 s[2:3], exec
	s_waitcnt lgkmcnt(0)
	s_barrier

; DN void gla_finish_item(const Params& p, int l, int b, int cs, int hh, char* smem) {
;     ...
;   for (int dir = 0; dir < 2; ++dir) {
;     vsync_l();
.LBB0_1010:
	s_waitcnt lgkmcnt(0)
	s_mov_b64 s[76:77], exec
	s_waitcnt lgkmcnt(0)
	s_barrier

; DI bfr f2bf(float x) { unsigned u = __float_as_uint(x); u += 0x7fffu + ((u >> 16) & 1u); return (bfr)(u >> 16); }
; DN void gla_finish_item(const Params& p, int l, int b, int cs, int hh, char* smem) {
;     ...
;     {
;       const float* Sg = GS + ((((size_t)b * 36 + cs) * 4 + hh) * 2 + dir) * 2048;
;       const int d = tid >> 3, e8 = (tid & 7) * 8;
;       float s8[8];
;       load8f(Sg + d * 64 + e8, s8);
; #pragma unroll
;       for (int e = 0; e < 8; ++e) StB[(e8 + e) * 40 + d] = f2bf(s8[e]);
;     }
;     vsync_l();
.LBB0_1016:
	s_or_b64 exec, exec, s[76:77]
	v_readlane_b32 s76, v253, 42
	s_or_b32 s76, s76, s84
	v_readlane_b32 s77, v253, 43
	s_lshl_b64 s[76:77], s[76:77], 13
	s_nop 0
	v_lshl_add_u64 v[28:29], v[46:47], 0, s[76:77]
	global_load_dwordx4 v[24:27], v[28:29], off offset:16
	s_nop 0
	global_load_dwordx4 v[28:31], v[28:29], off
	s_movk_i32 s76, 0x7fff
	s_waitcnt vmcnt(0)
	v_bfe_u32 v32, v28, 16, 1
	v_add3_u32 v28, v28, v32, s76
	ds_write_b16_d16_hi v49, v28 offset:10240
	v_bfe_u32 v28, v29, 16, 1
	v_add3_u32 v28, v29, v28, s76
	ds_write_b16_d16_hi v49, v28 offset:10320
	v_bfe_u32 v28, v30, 16, 1
	v_add3_u32 v28, v30, v28, s76
	ds_write_b16_d16_hi v63, v28 offset:10240
	v_bfe_u32 v28, v31, 16, 1
	v_add3_u32 v28, v31, v28, s76
	ds_write_b16_d16_hi v49, v28 offset:10480
	v_bfe_u32 v28, v24, 16, 1
	v_add3_u32 v24, v24, v28, s76
	ds_write_b16_d16_hi v64, v24 offset:10240
	v_bfe_u32 v24, v25, 16, 1
	v_add3_u32 v24, v25, v24, s76
	ds_write_b16_d16_hi v49, v24 offset:10640
	v_bfe_u32 v24, v26, 16, 1
	v_add3_u32 v24, v26, v24, s76
	ds_write_b16_d16_hi v65, v24 offset:10240
	v_bfe_u32 v24, v27, 16, 1
	v_add3_u32 v24, v27, v24, s76
	ds_write_b16_d16_hi v49, v24 offset:10800
	s_waitcnt lgkmcnt(0)
	s_mov_b64 s[76:77], exec
	s_waitcnt lgkmcnt(0)
	s_barrier

; DN void gla_finish_item(const Params& p, int l, int b, int cs, int hh, char* smem) {
;     ...
;       if (dir == 0) {
; #pragma unroll
;         for (int li = 1; li < 8; ++li) lgv[li] += lgv[li - 1];
;         segs[lgrp * 32 + dl] = lgv[7];
;       } else {
; #pragma unroll
;     ...
;         segs[lgrp * 32 + dl] = lgv[0];
;       }
;       vsync_l();
.LBB0_1025:
	ds_write_b32 v60, v34 offset:37120
	s_waitcnt lgkmcnt(0)
	s_mov_b64 s[84:85], exec
	s_waitcnt lgkmcnt(0)
	s_barrier

; DI unsigned pack2(float a, float b) { unsigned r; asm volatile("v_cvt_pk_bf16_f32 %0, %1, %2" : "=v"(r) : "v"(a), "v"(b)); return r; }
; DN void gla_finish_item(const Params& p, int l, int b, int cs, int hh, char* smem) {
;     ...
; #pragma unroll
;       for (int li = 0; li < 8; ++li) bb[(lgrp * 8 + li) * 33 + dl] = lgv[li] + off;
;     }
;     vsync_l();
;     {
;       float qo[8], ko[8];
; #pragma unroll
;       for (int e = 0; e < 8; ++e) {
;         const float bv = bb[li4 * 33 + d8 + e];
;         qo[e] = q8[e] * 0.17677669529663687f * __expf(bv);
;         ko[e] = k8[e] * __expf(-bv);
;       }
;       u32x4 qw, kw;
;       qw.x = pack2(qo[0], qo[1]); qw.y = pack2(qo[2], qo[3]); qw.z = pack2(qo[4], qo[5]); qw.w = pack2(qo[6], qo[7]);
;       kw.x = pack2(ko[0], ko[1]); kw.y = pack2(ko[2], ko[3]); kw.z = pack2(ko[4], ko[5]); kw.w = pack2(ko[6], ko[7]);
;       *(u32x4*)(QiB + li4 * 40 + d8) = qw;
;       *(u32x4*)(KiB + li4 * 40 + d8) = kw;
;     }
;     vsync_l();
.LBB0_1063:
	s_or_b64 exec, exec, s[84:85]
	s_waitcnt lgkmcnt(0)
	v_add_f32_e32 v25, v28, v24
	v_add_f32_e32 v28, v33, v24
	v_add_u32_e32 v33, 0x6000, v52
	ds_write2_b32 v33, v25, v28 offset1:33
	v_add_f32_e32 v25, v32, v24
	v_add_f32_e32 v28, v31, v24
	ds_write2_b32 v33, v25, v28 offset0:66 offset1:99
	v_add_f32_e32 v25, v30, v24
	v_add_f32_e32 v28, v29, v24
	ds_write2_b32 v33, v25, v28 offset0:132 offset1:165
	v_add_f32_e32 v25, v27, v24
	v_add_f32_e32 v24, v26, v24
	ds_write2_b32 v33, v25, v24 offset0:198 offset1:231
	s_waitcnt lgkmcnt(0)
	s_mov_b64 s[76:77], exec
	s_waitcnt lgkmcnt(0)
	s_barrier
.LBB0_1067:
	s_or_b64 exec, exec, s[76:77]
	v_lshlrev_b32_e32 v28, 16, v16
	v_and_b32_e32 v29, 0xffff0000, v16
	v_add_u32_e32 v16, 0x6000, v53
	v_lshlrev_b32_e32 v30, 16, v17
	v_and_b32_e32 v31, 0xffff0000, v17
	ds_read2_b32 v[16:17], v16 offset1:1
	v_lshlrev_b32_e32 v24, 16, v20
	v_and_b32_e32 v20, 0xffff0000, v20
	v_mul_f32_e32 v24, 0x3e3504f3, v24
	v_lshlrev_b32_e32 v25, 16, v21
	s_waitcnt lgkmcnt(0)
	v_mul_f32_e32 v34, 0x3fb8aa3b, v16
	v_mul_f32_e32 v16, 0xbfb8aa3b, v16
	v_exp_f32_e32 v16, v16
	v_exp_f32_e32 v34, v34
	v_and_b32_e32 v21, 0xffff0000, v21
	v_mul_f32_e32 v25, 0x3e3504f3, v25
	v_mul_f32_e32 v28, v16, v28
	v_mul_f32_e32 v16, 0x3e3504f3, v20
	v_mul_f32_e32 v20, 0x3fb8aa3b, v17
	v_exp_f32_e32 v20, v20
	v_mul_f32_e32 v24, v24, v34
	v_lshlrev_b32_e32 v26, 16, v22
	v_and_b32_e32 v22, 0xffff0000, v22
	v_mul_f32_e32 v20, v16, v20
	v_mul_f32_e32 v16, 0xbfb8aa3b, v17
	v_exp_f32_e32 v16, v16
	v_lshlrev_b32_e32 v32, 16, v18
	v_and_b32_e32 v18, 0xffff0000, v18
	v_mul_f32_e32 v26, 0x3e3504f3, v26
	v_mul_f32_e32 v29, v16, v29
	v_add_u32_e32 v16, 0x6008, v53
	ds_read2_b32 v[16:17], v16 offset1:1
	v_lshlrev_b32_e32 v27, 16, v23
	v_and_b32_e32 v23, 0xffff0000, v23
	v_lshlrev_b32_e32 v33, 16, v19
	v_and_b32_e32 v19, 0xffff0000, v19
	s_waitcnt lgkmcnt(0)
	v_mul_f32_e32 v34, 0x3fb8aa3b, v16
	v_mul_f32_e32 v16, 0xbfb8aa3b, v16
	v_exp_f32_e32 v16, v16
	v_exp_f32_e32 v34, v34
	v_mul_f32_e32 v30, v16, v30
	v_mul_f32_e32 v16, 0x3e3504f3, v21
	v_mul_f32_e32 v21, 0x3fb8aa3b, v17
	v_exp_f32_e32 v21, v21
	v_mul_f32_e32 v25, v25, v34
	v_mul_f32_e32 v21, v16, v21
	v_mul_f32_e32 v16, 0xbfb8aa3b, v17
	v_exp_f32_e32 v16, v16
	s_nop 0
	v_mul_f32_e32 v31, v16, v31
	v_add_u32_e32 v16, 0x6010, v53
	ds_read2_b32 v[16:17], v16 offset1:1
	s_waitcnt lgkmcnt(0)
	v_mul_f32_e32 v34, 0x3fb8aa3b, v16
	v_mul_f32_e32 v16, 0xbfb8aa3b, v16
	v_exp_f32_e32 v16, v16
	v_exp_f32_e32 v34, v34
	v_mul_f32_e32 v32, v16, v32
	v_mul_f32_e32 v16, 0x3e3504f3, v22
	v_mul_f32_e32 v22, 0x3fb8aa3b, v17
	v_exp_f32_e32 v22, v22
	v_mul_f32_e32 v26, v26, v34
	v_mul_f32_e32 v22, v16, v22
	v_mul_f32_e32 v16, 0xbfb8aa3b, v17
	v_exp_f32_e32 v16, v16
	s_nop 0
	v_mul_f32_e32 v34, v16, v18
	v_add_u32_e32 v16, 0x6018, v53
	ds_read2_b32 v[16:17], v16 offset1:1
	v_mul_f32_e32 v18, 0x3e3504f3, v27
	s_waitcnt lgkmcnt(0)
	v_mul_f32_e32 v27, 0x3fb8aa3b, v16
	v_exp_f32_e32 v27, v27
	v_mul_f32_e32 v16, 0xbfb8aa3b, v16
	v_exp_f32_e32 v16, v16
	v_mul_f32_e32 v27, v18, v27
	v_mul_f32_e32 v18, 0x3fb8aa3b, v17
	v_exp_f32_e32 v18, v18
	v_mul_f32_e32 v33, v16, v33
	v_mul_f32_e32 v16, 0x3e3504f3, v23
	v_mul_f32_e32 v23, v16, v18
	v_mul_f32_e32 v16, 0xbfb8aa3b, v17
	v_exp_f32_e32 v16, v16
	s_nop 0
	v_mul_f32_e32 v35, v16, v19
	v_cvt_pk_bf16_f32 v16, v24, v20
	v_cvt_pk_bf16_f32 v17, v25, v21
	v_cvt_pk_bf16_f32 v18, v26, v22
	v_cvt_pk_bf16_f32 v19, v27, v23
	v_cvt_pk_bf16_f32 v20, v28, v29
	v_cvt_pk_bf16_f32 v21, v30, v31
	v_cvt_pk_bf16_f32 v22, v32, v34
	v_cvt_pk_bf16_f32 v23, v33, v35
	ds_write_b128 v61, v[16:19]
	ds_write_b128 v61, v[20:23] offset:5120
	s_waitcnt lgkmcnt(0)
	s_mov_b64 s[76:77], exec
	s_waitcnt lgkmcnt(0)
	s_barrier
	s_branch .LBB0_1009

; DN void gla_finish_item(const Params& p, int l, int b, int cs, int hh, char* smem) {
;     ...
;   {
;     float ss = 0.f;
; #pragma unroll
;     for (int i = 0; i < 16; ++i) ss += accO[i] * accO[i];
;     ss += __shfl_xor(ss, 32);
;     if (h == 0) ssq[w * 32 + r] = ss;
;     vsync_l();
;     const float tot = ssq[w * 32 + r] + ssq[(w ^ 2) * 32 + r];
;     const float rstd = rsqrtf(tot * (1.f / 64.f) + 1e-6f);
.LBB0_1087:
	s_or_b64 exec, exec, s[2:3]
	s_waitcnt lgkmcnt(0)
	s_mov_b64 s[2:3], exec
	s_waitcnt lgkmcnt(0)
	s_barrier
	v_readlane_b32 s84, v253, 16
	v_readlane_b32 s94, v253, 18
	v_readlane_b32 s85, v253, 17
	s_movk_i32 s87, 0x80
	v_readlane_b32 s95, v253, 19
	s_movk_i32 s96, 0x1000
	s_movk_i32 s97, 0x90
	s_movk_i32 s67, 0x420
	s_mov_b64 s[74:75], 0x1000
	s_mov_b32 s81, s9
	v_readlane_b32 s70, v253, 34
	s_mov_b32 s77, s8
	v_readlane_b32 s12, v253, 36
	v_readlane_b32 s71, v253, 35
